# v93 + attention loops: back edge rotated in front of the loop-back barrier (barrier is the loop head, exit path has its own barrier copy)
# baseline (speedup 1.0000x reference)
; DI CP* kparams() { CP* kp = (CP*)__builtin_amdgcn_kernarg_segment_ptr(); asm volatile("" : "+s"(kp)); return kp; }
; DI int lane_id() { int l = __builtin_amdgcn_mbcnt_hi(-1, __builtin_amdgcn_mbcnt_lo(-1, 0)); asm volatile("" : "+v"(l)); return l; }
; #define A_LOAD(kt) do { const size_t ko = (size_t)(kt) * 64; st0 = *(const u32x4*)(kn_src + ko * 2048); st1 = *(const u32x4*)(kn_src + (ko + 32) * 2048); \
;         st2 = *(const u32x4*)(kr_src + ko * 64); st3 = *(const u32x4*)(v_src + ko); st4 = *(const u32x4*)(v_src + ko + (size_t)64 * 8192); } while (0)
; DI void attn_unit(LAS unsigned char* lds, int wid, int b, int h, int qb) {
;     CP& p = *kparams();
;     const int lane = lane_id(), tid = wid * 64 + lane, n = lane & 31, g = lane >> 5;
;     const int q0 = qb * 256 + wid * 32, cq = q0 >> 6, nkt = 4 * qb + 4;
;     const size_t tokq = (size_t)b * SEQ + q0 + n;
;     const bf16_t* Q = WSB(OFF_Q); const bf16_t* KN = WSB(OFF_KN); const bf16_t* KR = WSB(OFF_KR); const bf16_t* VT = WSB(OFF_VT2);
;     bf16x8 qf[12];
; #pragma unroll
;     for (int ks = 0; ks < 12; ++ks) qf[ks] = *(const bf16x8*)(Q + tokq * 3072 + h * 192 + ks * 16 + g * 8);
;     f32x16 o[4];
; #pragma unroll
;     for (int dt = 0; dt < 4; ++dt)
; #pragma unroll
;         for (int i = 0; i < 16; ++i) o[dt][i] = 0.f;
;     float mrow = -__builtin_inff(), lrow = 0.f;
;     const int krow = tid >> 4, kc16 = tid & 15, rrow = tid >> 3, rc8 = tid & 7;
;     const bf16_t* kn_src = KN + ((size_t)b * SEQ + krow) * 2048 + h * 128 + kc16 * 8;
;     const bf16_t* kr_src = KR + ((size_t)b * SEQ + rrow) * 64 + rc8 * 8;
;     const bf16_t* v_src = VT + ((size_t)h * 128 + rrow) * 8192 + (size_t)b * SEQ + rc8 * 8;
;     const int kn_dst = krow * KROW + kc16 * 16, kr_dst = rrow * KROW + 256 + rc8 * 16, v_dst = KBYTES + rrow * VROW + rc8 * 16;
;     u32x4 st0, st1, st2, st3, st4;
;     ...
;     A_LOAD(0); A_WRITE(0); __syncthreads();
.LBB0_1078:
	s_lshl_b32 s4, s55, 2
	s_and_b32 s4, s4, 28
	s_ashr_i32 s59, s55, 6
	s_mov_b64 s[16:17], s[0:1]
	v_mov_b32_e32 v183, v201
	s_add_i32 s4, s4, s59
	s_bfe_u32 s56, s55, 0x30003
	s_load_dwordx2 s[24:25], s[16:17], 0xa8
	s_ashr_i32 s22, s4, 4
	s_and_b32 s20, s4, 15
	s_xor_b32 s4, s56, 15
	s_lshl_b32 s18, s4, 8
	s_ashr_i32 s23, s22, 31
	s_lshr_b32 s57, s55, 3
	s_add_i32 s21, s18, s29
	s_lshl_b32 s61, s4, 2
	s_lshl_b64 s[16:17], s[22:23], 12
	v_and_b32_e32 v197, 31, v183
	s_add_u32 s26, s16, s21
	v_or_b32_e32 v0, s26, v197
	s_waitcnt lgkmcnt(0)
	v_mov_b64_e32 v[2:3], s[24:25]
	v_mad_u64_u32 v[2:3], s[18:19], v0, s37, v[2:3]
	v_add_u32_e32 v0, s28, v183
	v_ashrrev_i32_e32 v26, 3, v0
	v_ashrrev_i32_e32 v27, 31, v26
	s_addc_u32 s27, s17, 0
	s_mul_i32 s58, s20, 0xc0
	v_ashrrev_i32_e32 v24, 4, v0
	v_lshl_add_u64 v[4:5], s[16:17], 0, v[26:27]
	v_mad_i32_i24 v3, s27, v200, v3
	s_lshl_b32 s4, s58, 1
	v_ashrrev_i32_e32 v25, 31, v24
	v_lshlrev_b64 v[4:5], 7, v[4:5]
	v_lshlrev_b32_e32 v6, 4, v183
	v_lshl_add_u64 v[22:23], v[2:3], 0, s[4:5]
	v_lshl_add_u64 v[2:3], s[16:17], 0, v[24:25]
	s_lshl_b32 s4, s20, 7
	v_lshl_add_u64 v[4:5], s[24:25], 0, v[4:5]
	v_and_b32_e32 v28, 0x70, v6
	v_mov_b32_e32 v29, v1
	v_lshlrev_b64 v[2:3], 12, v[2:3]
	v_lshl_add_u64 v[10:11], v[4:5], 0, v[28:29]
	v_lshl_add_u64 v[4:5], v[26:27], 0, s[4:5]
	v_and_b32_e32 v32, 15, v183
	v_lshl_add_u64 v[2:3], s[24:25], 0, v[2:3]
	s_lshl_b32 s18, s20, 8
	s_mov_b32 s19, s5
	v_lshlrev_b64 v[4:5], 14, v[4:5]
	v_lshl_add_u64 v[2:3], v[2:3], 0, s[18:19]
	v_lshlrev_b32_e32 v0, 4, v32
	v_lshl_add_u64 v[4:5], s[24:25], 0, v[4:5]
	s_lshl_b64 s[18:19], s[22:23], 13
	v_lshl_add_u64 v[2:3], v[2:3], 0, v[0:1]
	v_lshl_add_u64 v[4:5], v[4:5], 0, s[18:19]
	v_lshl_add_u64 v[18:19], v[4:5], 0, v[28:29]
	v_add_co_u32_e32 v4, vcc, s40, v2
	v_ashrrev_i32_e32 v29, 5, v183
	s_nop 0
	v_addc_co_u32_e32 v5, vcc, 0, v3, vcc
	v_add_co_u32_e32 v6, vcc, s41, v2
	v_lshlrev_b32_e32 v184, 3, v29
	s_nop 0
	v_addc_co_u32_e32 v7, vcc, 0, v3, vcc
	v_add_co_u32_e32 v10, vcc, s42, v10
	v_ashrrev_i32_e32 v185, 31, v184
	s_nop 0
	v_addc_co_u32_e32 v11, vcc, 0, v11, vcc
	v_add_co_u32_e32 v14, vcc, s43, v18
	v_lshl_add_u64 v[22:23], v[184:185], 1, v[22:23]
	s_nop 0
	v_addc_co_u32_e32 v15, vcc, 0, v19, vcc
	v_add_co_u32_e32 v18, vcc, s44, v18
	global_load_dwordx4 v[2:5], v[4:5], off
	s_nop 0
	global_load_dwordx4 v[6:9], v[6:7], off
	v_addc_co_u32_e32 v19, vcc, 0, v19, vcc
	v_lshl_add_u64 v[30:31], v[22:23], 0, s[8:9]
	v_add_co_u32_e32 v22, vcc, s38, v22
	global_load_dwordx4 v[10:13], v[10:11], off
	s_nop 0
	v_addc_co_u32_e32 v23, vcc, 0, v23, vcc
	global_load_dwordx4 v[14:17], v[14:15], off
	s_lshr_b32 s62, s21, 6
	global_load_dwordx4 v[18:21], v[18:19], off
	s_nop 0
	global_load_dwordx4 v[138:141], v[30:31], off offset:32
	global_load_dwordx4 v[134:137], v[30:31], off offset:64
	global_load_dwordx4 v[130:133], v[30:31], off offset:96
	global_load_dwordx4 v[126:129], v[30:31], off offset:128
	global_load_dwordx4 v[122:125], v[30:31], off offset:160
	global_load_dwordx4 v[118:121], v[30:31], off offset:192
	global_load_dwordx4 v[114:117], v[30:31], off offset:224
	global_load_dwordx4 v[110:113], v[30:31], off offset:256
	global_load_dwordx4 v[106:109], v[30:31], off offset:288
	global_load_dwordx4 v[102:105], v[30:31], off offset:320
	global_load_dwordx4 v[142:145], v[22:23], off
	global_load_dwordx4 v[98:101], v[30:31], off offset:352
	v_mad_u64_u32 v[186:187], s[20:21], v24, s39, v[0:1]
	v_mad_u64_u32 v[188:189], s[20:21], v26, s39, v[28:29]
	v_add_u32_e32 v22, 0, v186
	s_and_b32 s20, s31, 12
	s_add_i32 s20, s20, s59
	s_and_b32 s60, s20, 15
	s_or_b32 s63, s61, 3
	s_waitcnt vmcnt(0)
	ds_write_b128 v22, v[2:5]
	ds_write_b128 v22, v[6:9] offset:12800
	v_add_u32_e32 v2, 0, v188
	v_mul_lo_u32 v3, v26, s45
	v_add_u32_e32 v198, v188, v3
	s_lshl_b32 s59, s60, 21
	s_add_u32 s20, s18, s59
	ds_write_b128 v2, v[10:13] offset:256
	v_add_u32_e32 v2, v2, v3
	v_add_u32_e32 v3, 0x6400, v2
	v_add_u32_e32 v2, 0x8600, v2
	ds_write2_b64 v3, v[14:15], v[16:17] offset1:1
	ds_write2_b64 v2, v[18:19], v[20:21] offset1:1
	v_lshlrev_b32_e32 v2, 2, v183
	v_xor_b32_e32 v185, 0x80, v2
	v_lshlrev_b64 v[2:3], 14, v[26:27]
	s_addc_u32 s21, s19, 0
	v_lshl_add_u64 v[190:191], s[20:21], 0, v[2:3]
	s_lshl_b64 s[20:21], s[22:23], 19
	s_add_u32 s20, s20, 0xe002000
	s_addc_u32 s21, s21, 0
	v_lshlrev_b64 v[2:3], 7, v[26:27]
	v_lshl_add_u64 v[192:193], s[20:21], 0, v[2:3]
	s_lshl_b64 s[22:23], s[22:23], 24
	v_lshlrev_b64 v[2:3], 12, v[24:25]
	v_mov_b32_e32 v16, v1
	v_mov_b32_e32 v17, v1
	v_lshlrev_b32_e32 v182, 3, v32
	v_lshlrev_b32_e32 v202, 4, v29
	v_or_b32_e32 v190, v190, v28
	v_or_b32_e32 v192, v192, v28
	v_lshl_add_u64 v[194:195], s[22:23], 0, v[2:3]
	s_lshl_b32 s60, s60, 8
	v_mov_b32_e32 v2, v1
	v_mov_b32_e32 v3, v1
	v_mov_b32_e32 v4, v1
	v_mov_b32_e32 v5, v1
	v_mov_b32_e32 v6, v1
	v_mov_b32_e32 v7, v1
	v_mov_b32_e32 v8, v1
	v_mov_b32_e32 v9, v1
	v_mov_b32_e32 v10, v1
	v_mov_b32_e32 v11, v1
	v_mov_b32_e32 v12, v1
	v_mov_b32_e32 v13, v1
	v_mov_b32_e32 v14, v1
	v_mov_b32_e32 v15, v1
	v_mov_b64_e32 v[32:33], v[16:17]
	v_mov_b64_e32 v[48:49], v[16:17]
	v_mov_b64_e32 v[64:65], v[16:17]
	v_mul_u32_u24_e32 v199, 0x190, v197
	v_mul_u32_u24_e32 v189, 0x88, v197
	v_or3_b32 v194, v194, s60, v0
	v_mov_b32_e32 v170, 0xff800000
	v_mov_b64_e32 v[30:31], v[14:15]
	v_mov_b64_e32 v[28:29], v[12:13]
	v_mov_b64_e32 v[26:27], v[10:11]
	v_mov_b64_e32 v[24:25], v[8:9]
	v_mov_b64_e32 v[22:23], v[6:7]
	v_mov_b64_e32 v[20:21], v[4:5]
	v_mov_b64_e32 v[18:19], v[2:3]
	v_mov_b64_e32 v[46:47], v[14:15]
	v_mov_b64_e32 v[44:45], v[12:13]
	v_mov_b64_e32 v[42:43], v[10:11]
	v_mov_b64_e32 v[40:41], v[8:9]
	v_mov_b64_e32 v[38:39], v[6:7]
	v_mov_b64_e32 v[36:37], v[4:5]
	v_mov_b64_e32 v[34:35], v[2:3]
	v_mov_b64_e32 v[62:63], v[14:15]
	v_mov_b64_e32 v[60:61], v[12:13]
	v_mov_b64_e32 v[58:59], v[10:11]
	v_mov_b64_e32 v[56:57], v[8:9]
	v_mov_b64_e32 v[54:55], v[6:7]
	v_mov_b64_e32 v[52:53], v[4:5]
	v_mov_b64_e32 v[50:51], v[2:3]
	v_mov_b32_e32 v187, 0
	s_mov_b32 s64, s5
	s_waitcnt lgkmcnt(0)
	v_mov_b32_e32 v216, 0
	v_mov_b32_e32 v217, 0
	v_mov_b32_e32 v218, 0
	v_mov_b32_e32 v219, 0
	v_mov_b32_e32 v220, 0
	v_mov_b32_e32 v221, 0
	v_mov_b32_e32 v222, 0
	v_mov_b32_e32 v223, 0
	v_mov_b32_e32 v224, 0
	v_mov_b32_e32 v225, 0
	v_mov_b32_e32 v226, 0
	v_mov_b32_e32 v227, 0
	v_mov_b32_e32 v228, 0
	v_mov_b32_e32 v229, 0
	v_mov_b32_e32 v230, 0
	v_mov_b32_e32 v231, 0
	s_add_u32 s70, s24, 0x11140000
	s_addc_u32 s71, s25, 0
	s_add_u32 s72, s24, 0x11160000
	s_addc_u32 s73, s25, 0
	s_add_u32 s74, s24, 0x13100000
	s_addc_u32 s75, s25, 0
	s_add_u32 s76, s24, 0x13200000
	s_addc_u32 s77, s25, 0
	s_mov_b64 s[78:79], s[24:25]
	v_add_u32_e32 v238, 0x6400, v198
	v_add_u32_e32 v239, 0x8600, v198
	v_add_u32_e32 v240, 0xa800, v238
	v_add_u32_e32 v241, 0xa800, v239
; #define LAS __attribute__((address_space(3)))
; DI float shfl_xor_l(float v, int lane, int m) { return __int_as_float(__builtin_amdgcn_ds_bpermute((lane ^ m) << 2, __float_as_int(v))); }
; #define A_LOAD(kt) do { const size_t ko = (size_t)(kt) * 64; st0 = *(const u32x4*)(kn_src + ko * 2048); st1 = *(const u32x4*)(kn_src + (ko + 32) * 2048); \
;         st2 = *(const u32x4*)(kr_src + ko * 64); st3 = *(const u32x4*)(v_src + ko); st4 = *(const u32x4*)(v_src + ko + (size_t)64 * 8192); } while (0)
; #define VLD(dst, j, dt) do { LAS unsigned char* va_ = vb + (32 * (dt) + n) * VROW + (16 * (j) + 4 * g) * 2; const u32x2 lo_ = *(const LAS u32x2*)(va_), hi_ = *(const LAS u32x2*)(va_ + 16); dst = (u32x4){lo_.x, lo_.y, hi_.x, hi_.y}; } while (0)
; DI void attn_unit(LAS unsigned char* lds, int wid, int b, int h, int qb) {
;     ...
;     for (int kt = 0; kt < nkt; ++kt) {
;         const int buf = kt & 1;
;         if (kt + 1 < nkt) A_LOAD(kt + 1);
;         if (kt <= cq) {
;             LAS unsigned char* kb = lds + buf * ABUF; LAS unsigned char* vb = kb + KBYTES;
;             f32x16 s0, s1;
; #pragma unroll
;             for (int i = 0; i < 16; ++i) { s0[i] = 0.f; s1[i] = 0.f; }
;     ...
;             bf16x8 ka[3][2];
;             ka[0][0] = KLD(0, 0); ka[0][1] = KLD(0, 1); ka[1][0] = KLD(1, 0); ka[1][1] = KLD(1, 1);
; #pragma unroll
;             for (int ks = 0; ks < 12; ++ks) {
;                 if (ks + 2 < 12) { ka[(ks + 2) % 3][0] = KLD(ks + 2, 0); ka[(ks + 2) % 3][1] = KLD(ks + 2, 1); }
;                 s0 = __builtin_amdgcn_mfma_f32_32x32x16_bf16(ka[ks % 3][0], qf[ks], s0, 0, 0, 0); s1 = __builtin_amdgcn_mfma_f32_32x32x16_bf16(ka[ks % 3][1], qf[ks], s1, 0, 0, 0);
;                 __builtin_amdgcn_sched_barrier(0); }
;             u32x4 vf[2][4];
; #pragma unroll
;             for (int dt = 0; dt < 4; ++dt) VLD(vf[0][dt], 0, dt);
;             float mx = s0[0];
; #pragma unroll
;             for (int i = 1; i < 16; ++i) mx = fmaxf(mx, s0[i]);
; #pragma unroll
;             for (int i = 0; i < 16; ++i) mx = fmaxf(mx, s1[i]);
;             mx = fmaxf(mx, shfl_xor_l(mx, lane, 32));
.Lrot0_head:
	s_barrier
.LBB0_1079:
	s_and_b32 s65, s64, 1
	global_load_dwordx4 v[146:149], v194, s[70:71]
	global_load_dwordx4 v[150:153], v194, s[72:73]
	global_load_dwordx4 v[154:157], v192, s[78:79]
	global_load_dwordx4 v[158:161], v190, s[74:75] offset:128
	global_load_dwordx4 v[162:165], v190, s[76:77] offset:128
	s_cmp_gt_u32 s64, s62
	s_cbranch_scc1 .LBB0_1083
	s_mul_i32 s66, s65, 0xa800
	s_add_i32 s66, s66, 0
	v_add3_u32 v171, s66, v199, v202
	ds_read_b128 v[66:69], v171
	ds_read_b128 v[166:169], v171 offset:32
	ds_read_b128 v[82:85], v171 offset:12800
	ds_read_b128 v[172:175], v171 offset:64
	ds_read_b128 v[176:179], v171 offset:12832
	ds_read_b128 v[204:207], v171 offset:12864
	s_waitcnt lgkmcnt(3)
	v_mfma_f32_32x32x16_bf16 v[82:97], v[82:85], v[142:145], v[216:231]
	v_mfma_f32_32x32x16_bf16 v[66:81], v[66:69], v[142:145], v[216:231]
	v_mfma_f32_32x32x16_bf16 v[66:81], v[166:169], v[138:141], v[66:81]
	ds_read_b128 v[166:169], v171 offset:96
	ds_read_b128 v[208:211], v171 offset:12896
	s_waitcnt lgkmcnt(3)
	v_mfma_f32_32x32x16_bf16 v[82:97], v[176:179], v[138:141], v[82:97]
	v_mfma_f32_32x32x16_bf16 v[66:81], v[172:175], v[134:137], v[66:81]
	ds_read_b128 v[172:175], v171 offset:128
	ds_read_b128 v[176:179], v171 offset:12928
	s_waitcnt lgkmcnt(4)
	v_mfma_f32_32x32x16_bf16 v[82:97], v[204:207], v[134:137], v[82:97]
	s_waitcnt lgkmcnt(3)
	v_mfma_f32_32x32x16_bf16 v[66:81], v[166:169], v[130:133], v[66:81]
	ds_read_b128 v[166:169], v171 offset:160
	ds_read_b128 v[204:207], v171 offset:12960
	s_waitcnt lgkmcnt(4)
	v_mfma_f32_32x32x16_bf16 v[82:97], v[208:211], v[130:133], v[82:97]
	s_waitcnt lgkmcnt(3)
	v_mfma_f32_32x32x16_bf16 v[66:81], v[172:175], v[126:129], v[66:81]
	ds_read_b128 v[172:175], v171 offset:192
	ds_read_b128 v[208:211], v171 offset:12992
	s_waitcnt lgkmcnt(4)
	v_mfma_f32_32x32x16_bf16 v[82:97], v[176:179], v[126:129], v[82:97]
	s_waitcnt lgkmcnt(3)
	v_mfma_f32_32x32x16_bf16 v[66:81], v[166:169], v[122:125], v[66:81]
	ds_read_b128 v[166:169], v171 offset:224
	ds_read_b128 v[176:179], v171 offset:13024
	s_waitcnt lgkmcnt(4)
	v_mfma_f32_32x32x16_bf16 v[82:97], v[204:207], v[122:125], v[82:97]
	s_waitcnt lgkmcnt(3)
	v_mfma_f32_32x32x16_bf16 v[66:81], v[172:175], v[118:121], v[66:81]
	ds_read_b128 v[172:175], v171 offset:256
	ds_read_b128 v[204:207], v171 offset:13056
	s_waitcnt lgkmcnt(4)
	v_mfma_f32_32x32x16_bf16 v[82:97], v[208:211], v[118:121], v[82:97]
	s_waitcnt lgkmcnt(3)
	v_mfma_f32_32x32x16_bf16 v[66:81], v[166:169], v[114:117], v[66:81]
	ds_read_b128 v[166:169], v171 offset:288
	ds_read_b128 v[208:211], v171 offset:13088
	s_waitcnt lgkmcnt(4)
	v_mfma_f32_32x32x16_bf16 v[82:97], v[176:179], v[114:117], v[82:97]
	s_waitcnt lgkmcnt(3)
	v_mfma_f32_32x32x16_bf16 v[66:81], v[172:175], v[110:113], v[66:81]
	ds_read_b128 v[172:175], v171 offset:320
	ds_read_b128 v[176:179], v171 offset:13120
	s_waitcnt lgkmcnt(4)
	v_mfma_f32_32x32x16_bf16 v[82:97], v[204:207], v[110:113], v[82:97]
	s_waitcnt lgkmcnt(3)
	v_mfma_f32_32x32x16_bf16 v[66:81], v[166:169], v[106:109], v[66:81]
	ds_read_b128 v[166:169], v171 offset:352
	ds_read_b128 v[212:215], v171 offset:13152
	s_waitcnt lgkmcnt(4)
	v_mfma_f32_32x32x16_bf16 v[82:97], v[208:211], v[106:109], v[82:97]
	s_waitcnt lgkmcnt(3)
	v_mfma_f32_32x32x16_bf16 v[66:81], v[172:175], v[102:105], v[66:81]
	s_waitcnt lgkmcnt(2)
	v_mfma_f32_32x32x16_bf16 v[82:97], v[176:179], v[102:105], v[82:97]
	s_waitcnt lgkmcnt(1)
	v_mfma_f32_32x32x16_bf16 v[66:81], v[166:169], v[98:101], v[66:81]
	v_add3_u32 v171, s66, v184, v189
	v_add_u32_e32 v204, 0x6000, v171
	v_add_u32_e32 v205, 0x7000, v171
	v_add_u32_e32 v206, 0x8000, v171
	v_add_u32_e32 v207, 0x9000, v171
	ds_read2_b64 v[166:169], v204 offset0:128 offset1:130
	s_nop 4
	v_max_f32_e32 v172, v66, v67
	s_waitcnt lgkmcnt(1)
	v_mfma_f32_32x32x16_bf16 v[82:97], v[212:215], v[98:101], v[82:97]
	v_max3_f32 v172, v172, v68, v69
	v_max3_f32 v172, v172, v70, v71
	v_max3_f32 v172, v172, v72, v73
	v_max3_f32 v172, v172, v74, v75
	v_max3_f32 v172, v172, v76, v77
	v_max3_f32 v172, v172, v78, v79
	v_max3_f32 v172, v172, v80, v81
	s_nop 4
	v_max3_f32 v172, v172, v82, v83
	v_max3_f32 v172, v172, v84, v85
	v_max3_f32 v172, v172, v86, v87
	v_max3_f32 v172, v172, v88, v89
	v_max3_f32 v172, v172, v90, v91
	v_max3_f32 v172, v172, v92, v93
	v_max3_f32 v172, v172, v94, v95
	v_max3_f32 v172, v172, v96, v97
	ds_read2_b64 v[178:181], v205 offset0:160 offset1:162
	ds_read2_b64 v[174:177], v206 offset0:192 offset1:194
	v_cmp_lt_f32_e32 vcc, 0x41000000, v172
	s_cmp_eq_u32 s64, 0
	s_cbranch_scc1 .Lfold_0_upd
	s_cbranch_vccnz .Lfold_0_upd

; DI void attn_unit(LAS unsigned char* lds, int wid, int b, int h, int qb) {
;     ...
;         if (kt + 1 < nkt) A_WRITE(buf ^ 1);
;         __syncthreads();
.Lw1_join:
	s_cmp_eq_u32 s63, s64
	s_waitcnt lgkmcnt(0)
	s_cbranch_scc1 .Lrot0_exit
	s_branch .Lrot0_head

; DI void attn_unit(LAS unsigned char* lds, int wid, int b, int h, int qb) {
;     ...
;             if (__builtin_amdgcn_ballot_w64(alpha != 1.f) != 0ull) {
; #pragma unroll
;                 for (int dt = 0; dt < 4; ++dt)
; #pragma unroll
;                     for (int i = 0; i < 16; ++i) o[dt][i] *= alpha;
;             }
;     ...
;         __syncthreads();
.Lfold_0_go:
	s_nop 0
	v_pk_mul_f32 v[64:65], v[64:65], v[196:197] op_sel_hi:[1,0]
	v_pk_mul_f32 v[62:63], v[62:63], v[196:197] op_sel_hi:[1,0]
	v_pk_mul_f32 v[60:61], v[60:61], v[196:197] op_sel_hi:[1,0]
	v_pk_mul_f32 v[58:59], v[58:59], v[196:197] op_sel_hi:[1,0]
	v_pk_mul_f32 v[56:57], v[56:57], v[196:197] op_sel_hi:[1,0]
	v_pk_mul_f32 v[54:55], v[54:55], v[196:197] op_sel_hi:[1,0]
	v_pk_mul_f32 v[52:53], v[52:53], v[196:197] op_sel_hi:[1,0]
	v_pk_mul_f32 v[50:51], v[50:51], v[196:197] op_sel_hi:[1,0]
	v_pk_mul_f32 v[48:49], v[48:49], v[196:197] op_sel_hi:[1,0]
	v_pk_mul_f32 v[46:47], v[46:47], v[196:197] op_sel_hi:[1,0]
	v_pk_mul_f32 v[44:45], v[44:45], v[196:197] op_sel_hi:[1,0]
	v_pk_mul_f32 v[42:43], v[42:43], v[196:197] op_sel_hi:[1,0]
	v_pk_mul_f32 v[40:41], v[40:41], v[196:197] op_sel_hi:[1,0]
	v_pk_mul_f32 v[38:39], v[38:39], v[196:197] op_sel_hi:[1,0]
	v_pk_mul_f32 v[36:37], v[36:37], v[196:197] op_sel_hi:[1,0]
	v_pk_mul_f32 v[34:35], v[34:35], v[196:197] op_sel_hi:[1,0]
	v_pk_mul_f32 v[32:33], v[32:33], v[196:197] op_sel_hi:[1,0]
	v_pk_mul_f32 v[30:31], v[30:31], v[196:197] op_sel_hi:[1,0]
	v_pk_mul_f32 v[28:29], v[28:29], v[196:197] op_sel_hi:[1,0]
	v_pk_mul_f32 v[26:27], v[26:27], v[196:197] op_sel_hi:[1,0]
	v_pk_mul_f32 v[24:25], v[24:25], v[196:197] op_sel_hi:[1,0]
	v_pk_mul_f32 v[22:23], v[22:23], v[196:197] op_sel_hi:[1,0]
	v_pk_mul_f32 v[20:21], v[20:21], v[196:197] op_sel_hi:[1,0]
	v_pk_mul_f32 v[18:19], v[18:19], v[196:197] op_sel_hi:[1,0]
	v_pk_mul_f32 v[16:17], v[16:17], v[196:197] op_sel_hi:[1,0]
	v_pk_mul_f32 v[14:15], v[14:15], v[196:197] op_sel_hi:[1,0]
	v_pk_mul_f32 v[12:13], v[12:13], v[196:197] op_sel_hi:[1,0]
	v_pk_mul_f32 v[10:11], v[10:11], v[196:197] op_sel_hi:[1,0]
	v_pk_mul_f32 v[8:9], v[8:9], v[196:197] op_sel_hi:[1,0]
	v_pk_mul_f32 v[6:7], v[6:7], v[196:197] op_sel_hi:[1,0]
	v_pk_mul_f32 v[4:5], v[4:5], v[196:197] op_sel_hi:[1,0]
	v_pk_mul_f32 v[2:3], v[2:3], v[196:197] op_sel_hi:[1,0]
	v_sub_f32_e32 v66, v66, v237
	v_sub_f32_e32 v82, v82, v237
	v_sub_f32_e32 v67, v67, v237
	v_sub_f32_e32 v83, v83, v237
	v_sub_f32_e32 v68, v68, v237
	v_sub_f32_e32 v84, v84, v237
	v_sub_f32_e32 v69, v69, v237
	v_sub_f32_e32 v85, v85, v237
	v_sub_f32_e32 v70, v70, v237
	v_sub_f32_e32 v86, v86, v237
	v_sub_f32_e32 v71, v71, v237
	v_sub_f32_e32 v87, v87, v237
	v_sub_f32_e32 v72, v72, v237
	v_sub_f32_e32 v88, v88, v237
	v_sub_f32_e32 v73, v73, v237
	v_sub_f32_e32 v89, v89, v237
	v_sub_f32_e32 v74, v74, v237
	v_sub_f32_e32 v90, v90, v237
	v_sub_f32_e32 v75, v75, v237
	v_sub_f32_e32 v91, v91, v237
	v_sub_f32_e32 v76, v76, v237
	v_sub_f32_e32 v92, v92, v237
	v_sub_f32_e32 v77, v77, v237
	v_sub_f32_e32 v93, v93, v237
	v_sub_f32_e32 v78, v78, v237
	v_sub_f32_e32 v94, v94, v237
	v_sub_f32_e32 v79, v79, v237
	v_sub_f32_e32 v95, v95, v237
	v_sub_f32_e32 v80, v80, v237
	v_sub_f32_e32 v96, v96, v237
	v_sub_f32_e32 v81, v81, v237
	v_sub_f32_e32 v97, v97, v237
	v_sub_f32_e32 v216, v216, v237
	v_sub_f32_e32 v217, v217, v237
	v_sub_f32_e32 v218, v218, v237
	v_sub_f32_e32 v219, v219, v237
	v_sub_f32_e32 v220, v220, v237
	v_sub_f32_e32 v221, v221, v237
	v_sub_f32_e32 v222, v222, v237
	v_sub_f32_e32 v223, v223, v237
	v_sub_f32_e32 v224, v224, v237
	v_sub_f32_e32 v225, v225, v237
	v_sub_f32_e32 v226, v226, v237
	v_sub_f32_e32 v227, v227, v237
	v_sub_f32_e32 v228, v228, v237
	v_sub_f32_e32 v229, v229, v237
	v_sub_f32_e32 v230, v230, v237
	v_sub_f32_e32 v231, v231, v237
	v_mul_f32_e32 v187, v187, v196
	s_branch .LBB0_1082
.Lrot0_exit:
	s_barrier
; #define LAS __attribute__((address_space(3)))
; DI float shfl_xor_l(float v, int lane, int m) { return __int_as_float(__builtin_amdgcn_ds_bpermute((lane ^ m) << 2, __float_as_int(v))); }
; #define A_LOAD(kt) do { const size_t ko = (size_t)(kt) * 64; st0 = *(const u32x4*)(kn_src + ko * 2048); st1 = *(const u32x4*)(kn_src + (ko + 32) * 2048); \
;         st2 = *(const u32x4*)(kr_src + ko * 64); st3 = *(const u32x4*)(v_src + ko); st4 = *(const u32x4*)(v_src + ko + (size_t)64 * 8192); } while (0)
; #define VLD(dst, j, dt) do { LAS unsigned char* va_ = vb + (32 * (dt) + n) * VROW + (16 * (j) + 4 * g) * 2; const u32x2 lo_ = *(const LAS u32x2*)(va_), hi_ = *(const LAS u32x2*)(va_ + 16); dst = (u32x4){lo_.x, lo_.y, hi_.x, hi_.y}; } while (0)
; DI void attn_unit(LAS unsigned char* lds, int wid, int b, int h, int qb) {
;     ...
;         if (kt + 1 < nkt) A_LOAD(kt + 1);
;         if (kt <= cq) {
;             LAS unsigned char* kb = lds + buf * ABUF; LAS unsigned char* vb = kb + KBYTES;
;             f32x16 s0, s1;
; #pragma unroll
;             for (int i = 0; i < 16; ++i) { s0[i] = 0.f; s1[i] = 0.f; }
;     ...
;             bf16x8 ka[3][2];
;             ka[0][0] = KLD(0, 0); ka[0][1] = KLD(0, 1); ka[1][0] = KLD(1, 0); ka[1][1] = KLD(1, 1);
; #pragma unroll
;             for (int ks = 0; ks < 12; ++ks) {
;                 if (ks + 2 < 12) { ka[(ks + 2) % 3][0] = KLD(ks + 2, 0); ka[(ks + 2) % 3][1] = KLD(ks + 2, 1); }
;                 s0 = __builtin_amdgcn_mfma_f32_32x32x16_bf16(ka[ks % 3][0], qf[ks], s0, 0, 0, 0); s1 = __builtin_amdgcn_mfma_f32_32x32x16_bf16(ka[ks % 3][1], qf[ks], s1, 0, 0, 0);
;                 __builtin_amdgcn_sched_barrier(0); }
;             u32x4 vf[2][4];
; #pragma unroll
;             for (int dt = 0; dt < 4; ++dt) VLD(vf[0][dt], 0, dt);
;             float mx = s0[0];
; #pragma unroll
;             for (int i = 1; i < 16; ++i) mx = fmaxf(mx, s0[i]);
; #pragma unroll
;             for (int i = 0; i < 16; ++i) mx = fmaxf(mx, s1[i]);
;             mx = fmaxf(mx, shfl_xor_l(mx, lane, 32));
.LBB0_1086:
	s_or_b32 s61, s61, 2
	s_cmp_ge_u32 s61, s62
	s_cbranch_scc1 .LBB0_1090
	s_bitcmp1_b32 s63, 0
	s_cselect_b32 s61, 0xa800, 0
	s_add_i32 s61, s61, 0
	v_add3_u32 v162, s61, v199, v202
	ds_read_b128 v[66:69], v162
	ds_read_b128 v[146:149], v162 offset:32
	ds_read_b128 v[82:85], v162 offset:12800
	ds_read_b128 v[150:153], v162 offset:64
	ds_read_b128 v[154:157], v162 offset:12832
	ds_read_b128 v[158:161], v162 offset:12864
	s_waitcnt lgkmcnt(3)
	v_mfma_f32_32x32x16_bf16 v[82:97], v[82:85], v[142:145], v[216:231]
	v_mfma_f32_32x32x16_bf16 v[66:81], v[66:69], v[142:145], v[216:231]
	v_mfma_f32_32x32x16_bf16 v[66:81], v[146:149], v[138:141], v[66:81]
	ds_read_b128 v[142:145], v162 offset:96
	ds_read_b128 v[146:149], v162 offset:12896
	s_waitcnt lgkmcnt(3)
	v_mfma_f32_32x32x16_bf16 v[82:97], v[154:157], v[138:141], v[82:97]
	v_mfma_f32_32x32x16_bf16 v[66:81], v[150:153], v[134:137], v[66:81]
	ds_read_b128 v[138:141], v162 offset:128
	ds_read_b128 v[150:153], v162 offset:12928
	s_waitcnt lgkmcnt(4)
	v_mfma_f32_32x32x16_bf16 v[82:97], v[158:161], v[134:137], v[82:97]
	s_waitcnt lgkmcnt(3)
	v_mfma_f32_32x32x16_bf16 v[66:81], v[142:145], v[130:133], v[66:81]
	ds_read_b128 v[134:137], v162 offset:160
	ds_read_b128 v[142:145], v162 offset:12960
	s_waitcnt lgkmcnt(4)
	v_mfma_f32_32x32x16_bf16 v[82:97], v[146:149], v[130:133], v[82:97]
	s_waitcnt lgkmcnt(3)
	v_mfma_f32_32x32x16_bf16 v[66:81], v[138:141], v[126:129], v[66:81]
	ds_read_b128 v[130:133], v162 offset:192
	ds_read_b128 v[138:141], v162 offset:12992
	s_waitcnt lgkmcnt(4)
	v_mfma_f32_32x32x16_bf16 v[82:97], v[150:153], v[126:129], v[82:97]
	s_waitcnt lgkmcnt(3)
	v_mfma_f32_32x32x16_bf16 v[66:81], v[134:137], v[122:125], v[66:81]
	ds_read_b128 v[126:129], v162 offset:224
	ds_read_b128 v[134:137], v162 offset:13024
	s_waitcnt lgkmcnt(4)
	v_mfma_f32_32x32x16_bf16 v[82:97], v[142:145], v[122:125], v[82:97]
	s_waitcnt lgkmcnt(3)
	v_mfma_f32_32x32x16_bf16 v[66:81], v[130:133], v[118:121], v[66:81]
	ds_read_b128 v[122:125], v162 offset:256
	ds_read_b128 v[130:133], v162 offset:13056
	s_waitcnt lgkmcnt(4)
	v_mfma_f32_32x32x16_bf16 v[82:97], v[138:141], v[118:121], v[82:97]
	s_waitcnt lgkmcnt(3)
	v_mfma_f32_32x32x16_bf16 v[66:81], v[126:129], v[114:117], v[66:81]
	ds_read_b128 v[118:121], v162 offset:288
	ds_read_b128 v[126:129], v162 offset:13088
	s_waitcnt lgkmcnt(4)
	v_mfma_f32_32x32x16_bf16 v[82:97], v[134:137], v[114:117], v[82:97]
	s_waitcnt lgkmcnt(3)
	v_mfma_f32_32x32x16_bf16 v[66:81], v[122:125], v[110:113], v[66:81]
	ds_read_b128 v[114:117], v162 offset:320
	ds_read_b128 v[122:125], v162 offset:13120
	s_waitcnt lgkmcnt(4)
	v_mfma_f32_32x32x16_bf16 v[82:97], v[130:133], v[110:113], v[82:97]
	s_waitcnt lgkmcnt(3)
	v_mfma_f32_32x32x16_bf16 v[66:81], v[118:121], v[106:109], v[66:81]
	ds_read_b128 v[110:113], v162 offset:352
	ds_read_b128 v[118:121], v162 offset:13152
	s_waitcnt lgkmcnt(4)
	v_mfma_f32_32x32x16_bf16 v[82:97], v[126:129], v[106:109], v[82:97]
	s_waitcnt lgkmcnt(3)
	v_mfma_f32_32x32x16_bf16 v[66:81], v[114:117], v[102:105], v[66:81]
	s_waitcnt lgkmcnt(2)
	v_mfma_f32_32x32x16_bf16 v[82:97], v[122:125], v[102:105], v[82:97]
	s_waitcnt lgkmcnt(1)
	v_mfma_f32_32x32x16_bf16 v[66:81], v[110:113], v[98:101], v[66:81]
	v_add_u32_e32 v102, s61, v184
	v_add_u32_e32 v122, v102, v189
	v_add_u32_e32 v115, 0x6000, v122
	v_add_u32_e32 v116, 0x7000, v122
	v_add_u32_e32 v117, 0x8000, v122
	ds_read2_b64 v[102:105], v115 offset0:128 offset1:130
	ds_read2_b64 v[110:113], v116 offset0:160 offset1:162
	s_nop 4
	v_max_f32_e32 v106, v66, v67
	s_waitcnt lgkmcnt(2)
	v_mfma_f32_32x32x16_bf16 v[82:97], v[118:121], v[98:101], v[82:97]
	v_max3_f32 v106, v106, v68, v69
	v_max3_f32 v106, v106, v70, v71
	v_max3_f32 v106, v106, v72, v73
	v_max3_f32 v106, v106, v74, v75
	v_max3_f32 v106, v106, v76, v77
	v_max3_f32 v106, v106, v78, v79
	v_max3_f32 v106, v106, v80, v81
	s_nop 4
	v_max3_f32 v98, v106, v82, v83
	v_max3_f32 v98, v98, v84, v85
	v_max3_f32 v98, v98, v86, v87
	v_max3_f32 v98, v98, v88, v89
	v_max3_f32 v98, v98, v90, v91
	v_max3_f32 v98, v98, v92, v93
	v_max3_f32 v98, v98, v94, v95
	v_max3_f32 v98, v98, v96, v97
	ds_bpermute_b32 v99, v185, v98
	v_add_u32_e32 v118, 0x9000, v122
	ds_read2_b64 v[106:109], v117 offset0:192 offset1:194
	s_waitcnt lgkmcnt(1)
	v_max_f32_e32 v237, v98, v99
	v_cmp_lt_f32_e32 vcc, 0x41000000, v237
	ds_read2_b64 v[98:101], v118 offset0:224 offset1:226
	s_cbranch_vccz .Lfold_1_keep

; #define LAS __attribute__((address_space(3)))
; DI u32x2 pk4(f32x4 v) { u32x2 r; r.x = pk2(v[0], v[1]); r.y = pk2(v[2], v[3]); return r; }
; DI float shfl_xor_l(float v, int lane, int m) { return __int_as_float(__builtin_amdgcn_ds_bpermute((lane ^ m) << 2, __float_as_int(v))); }
; DI void attn_unit(LAS unsigned char* lds, int wid, int b, int h, int qb) {
;     ...
;     const float lt = lrow + shfl_xor_l(lrow, lane, 32), inv = 1.f / lt;
;     LAS unsigned char* pt_ = lds + ABUF + wid * (32 * 272);
; #pragma unroll
;     for (int dt = 0; dt < 4; ++dt)
; #pragma unroll
;         for (int blk = 0; blk < 4; ++blk) { const f32x4 v = {o[dt][4 * blk] * inv, o[dt][4 * blk + 1] * inv, o[dt][4 * blk + 2] * inv, o[dt][4 * blk + 3] * inv};
;             *(LAS u32x2*)(pt_ + n * 272 + (32 * dt + 8 * blk + 4 * g) * 2) = pk4(v); }
;     asm volatile("" ::: "memory");
;     bf16_t* od = WSB(OFF_O) + ((size_t)b * SEQ + q0 + (lane >> 4)) * 2048 + h * 128 + (lane & 15) * 8;
; #pragma unroll
;     for (int j = 0; j < 8; ++j) { const u32x4 w = *(const LAS u32x4*)(pt_ + (4 * j + (lane >> 4)) * 272 + (lane & 15) * 16); *(u32x4*)(od + (size_t)(4 * j) * 2048) = w; }
;     asm volatile("" ::: "memory");
.LBB0_1090:
	ds_bpermute_b32 v66, v185, v187
	s_waitcnt lgkmcnt(0)
	s_barrier
	v_mov_b32_e32 v185, v1
	v_add_f32_e32 v66, v187, v66
	v_div_scale_f32 v67, s[62:63], v66, v66, 1.0
	v_rcp_f32_e32 v68, v67
	v_div_scale_f32 v69, vcc, 1.0, v66, 1.0
	v_mov_b32_e32 v187, v201
	v_fma_f32 v70, -v67, v68, 1.0
	v_fmac_f32_e32 v68, v70, v68
	v_mul_f32_e32 v70, v69, v68
	v_fma_f32 v71, -v67, v70, v69
	v_fmac_f32_e32 v70, v71, v68
	v_fma_f32 v67, -v67, v70, v69
	v_div_fmas_f32 v67, v67, v68, v70
	v_div_fixup_f32 v66, v67, v66, 1.0
	v_mul_u32_u24_e32 v67, 0x110, v197
	v_add3_u32 v67, s30, v67, v184
	v_pk_mul_f32 v[2:3], v[2:3], v[66:67] op_sel_hi:[1,0]
	v_pk_mul_f32 v[4:5], v[4:5], v[66:67] op_sel_hi:[1,0]
	v_pk_mul_f32 v[50:51], v[50:51], v[66:67] op_sel_hi:[1,0]
	v_pk_mul_f32 v[52:53], v[52:53], v[66:67] op_sel_hi:[1,0]
	v_cvt_pk_bf16_f32 v2, v2, v3
	v_cvt_pk_bf16_f32 v3, v4, v5
	v_pk_mul_f32 v[4:5], v[6:7], v[66:67] op_sel_hi:[1,0]
	v_pk_mul_f32 v[6:7], v[8:9], v[66:67] op_sel_hi:[1,0]
	v_cvt_pk_bf16_f32 v50, v50, v51
	v_cvt_pk_bf16_f32 v51, v52, v53
	v_pk_mul_f32 v[52:53], v[54:55], v[66:67] op_sel_hi:[1,0]
	v_pk_mul_f32 v[54:55], v[56:57], v[66:67] op_sel_hi:[1,0]
	v_add_u32_e32 v56, 0xa800, v67
	v_cvt_pk_bf16_f32 v4, v4, v5
	v_cvt_pk_bf16_f32 v5, v6, v7
	ds_write2_b64 v56, v[2:3], v[4:5] offset0:24 offset1:26
	v_pk_mul_f32 v[2:3], v[10:11], v[66:67] op_sel_hi:[1,0]
	v_pk_mul_f32 v[4:5], v[12:13], v[66:67] op_sel_hi:[1,0]
	v_pk_mul_f32 v[34:35], v[34:35], v[66:67] op_sel_hi:[1,0]
	v_pk_mul_f32 v[36:37], v[36:37], v[66:67] op_sel_hi:[1,0]
	v_pk_mul_f32 v[18:19], v[18:19], v[66:67] op_sel_hi:[1,0]
	v_pk_mul_f32 v[20:21], v[20:21], v[66:67] op_sel_hi:[1,0]
	v_cvt_pk_bf16_f32 v2, v2, v3
	v_cvt_pk_bf16_f32 v3, v4, v5
	v_pk_mul_f32 v[4:5], v[14:15], v[66:67] op_sel_hi:[1,0]
	v_pk_mul_f32 v[6:7], v[16:17], v[66:67] op_sel_hi:[1,0]
	v_cvt_pk_bf16_f32 v34, v34, v35
	v_cvt_pk_bf16_f32 v35, v36, v37
	v_pk_mul_f32 v[36:37], v[38:39], v[66:67] op_sel_hi:[1,0]
	v_pk_mul_f32 v[38:39], v[40:41], v[66:67] op_sel_hi:[1,0]
	v_cvt_pk_bf16_f32 v18, v18, v19
	v_cvt_pk_bf16_f32 v19, v20, v21
	v_pk_mul_f32 v[20:21], v[22:23], v[66:67] op_sel_hi:[1,0]
	v_pk_mul_f32 v[22:23], v[24:25], v[66:67] op_sel_hi:[1,0]
	v_cvt_pk_bf16_f32 v4, v4, v5
	v_cvt_pk_bf16_f32 v5, v6, v7
	v_cvt_pk_bf16_f32 v52, v52, v53
	v_cvt_pk_bf16_f32 v53, v54, v55
	v_cvt_pk_bf16_f32 v36, v36, v37
	v_cvt_pk_bf16_f32 v37, v38, v39
	v_cvt_pk_bf16_f32 v20, v20, v21
	v_cvt_pk_bf16_f32 v21, v22, v23
	ds_write2_b64 v56, v[2:3], v[4:5] offset0:28 offset1:30
	v_ashrrev_i32_e32 v2, 4, v183
	ds_write2_b64 v56, v[50:51], v[52:53] offset1:2
	v_pk_mul_f32 v[50:51], v[58:59], v[66:67] op_sel_hi:[1,0]
	v_pk_mul_f32 v[52:53], v[60:61], v[66:67] op_sel_hi:[1,0]
	ds_write2_b64 v56, v[34:35], v[36:37] offset0:8 offset1:10
	v_pk_mul_f32 v[34:35], v[42:43], v[66:67] op_sel_hi:[1,0]
	v_pk_mul_f32 v[36:37], v[44:45], v[66:67] op_sel_hi:[1,0]
	ds_write2_b64 v56, v[18:19], v[20:21] offset0:16 offset1:18
	v_pk_mul_f32 v[18:19], v[26:27], v[66:67] op_sel_hi:[1,0]
	v_pk_mul_f32 v[20:21], v[28:29], v[66:67] op_sel_hi:[1,0]
	v_ashrrev_i32_e32 v3, 31, v2
	v_cvt_pk_bf16_f32 v50, v50, v51
	v_cvt_pk_bf16_f32 v51, v52, v53
	v_pk_mul_f32 v[52:53], v[62:63], v[66:67] op_sel_hi:[1,0]
	v_pk_mul_f32 v[54:55], v[64:65], v[66:67] op_sel_hi:[1,0]
	v_cvt_pk_bf16_f32 v34, v34, v35
	v_cvt_pk_bf16_f32 v35, v36, v37
	v_pk_mul_f32 v[36:37], v[46:47], v[66:67] op_sel_hi:[1,0]
	v_pk_mul_f32 v[38:39], v[48:49], v[66:67] op_sel_hi:[1,0]
	v_cvt_pk_bf16_f32 v18, v18, v19
	v_cvt_pk_bf16_f32 v19, v20, v21
	v_pk_mul_f32 v[20:21], v[30:31], v[66:67] op_sel_hi:[1,0]
	v_pk_mul_f32 v[22:23], v[32:33], v[66:67] op_sel_hi:[1,0]
	v_lshl_add_u64 v[4:5], s[26:27], 0, v[2:3]
	v_cvt_pk_bf16_f32 v52, v52, v53
	v_cvt_pk_bf16_f32 v53, v54, v55
	v_cvt_pk_bf16_f32 v36, v36, v37
	v_cvt_pk_bf16_f32 v37, v38, v39
	v_cvt_pk_bf16_f32 v20, v20, v21
	v_cvt_pk_bf16_f32 v21, v22, v23
	v_lshlrev_b64 v[4:5], 12, v[4:5]
	ds_write2_b64 v56, v[50:51], v[52:53] offset0:4 offset1:6
	ds_write2_b64 v56, v[34:35], v[36:37] offset0:12 offset1:14
	ds_write2_b64 v56, v[18:19], v[20:21] offset0:20 offset1:22
	v_lshl_add_u64 v[4:5], s[24:25], 0, v[4:5]
	s_lshl_b32 s24, s4, 1
	s_mov_b32 s25, s5
	v_mul_lo_u32 v2, v2, s46
	v_lshl_add_u64 v[4:5], v[4:5], 0, s[24:25]
	v_lshlrev_b32_e32 v6, 1, v182
	v_mov_b32_e32 v7, v1
	v_add3_u32 v0, s30, v0, v2
	v_lshl_add_u64 v[10:11], v[4:5], 0, v[6:7]
	ds_read_b128 v[2:5], v0 offset:43008
	ds_read_b128 v[6:9], v0 offset:44096
	v_add_co_u32_e32 v12, vcc, s47, v10
	s_mov_b64 s[26:27], s[0:1]
	s_nop 0
	v_addc_co_u32_e32 v13, vcc, 0, v11, vcc
	s_waitcnt lgkmcnt(1)
	global_store_dwordx4 v[12:13], v[2:5], off
	v_mov_b32_e32 v172, 0xff800000
	s_nop 0
	v_add_co_u32_e32 v2, vcc, s48, v10
	s_nop 1
	v_addc_co_u32_e32 v3, vcc, 0, v11, vcc
	s_waitcnt lgkmcnt(0)
	global_store_dwordx4 v[2:3], v[6:9], off
	ds_read_b128 v[2:5], v0 offset:45184
	ds_read_b128 v[6:9], v0 offset:46272
	v_add_co_u32_e32 v12, vcc, s49, v10
	s_nop 1
	v_addc_co_u32_e32 v13, vcc, 0, v11, vcc
	s_waitcnt lgkmcnt(1)
	global_store_dwordx4 v[12:13], v[2:5], off
	s_nop 1
	v_add_co_u32_e32 v2, vcc, s50, v10
	s_nop 1
	v_addc_co_u32_e32 v3, vcc, 0, v11, vcc
	s_waitcnt lgkmcnt(0)
	global_store_dwordx4 v[2:3], v[6:9], off
	ds_read_b128 v[2:5], v0 offset:47360
	ds_read_b128 v[6:9], v0 offset:48448
	v_add_co_u32_e32 v12, vcc, s51, v10
	s_nop 1
	v_addc_co_u32_e32 v13, vcc, 0, v11, vcc
	s_waitcnt lgkmcnt(1)
	global_store_dwordx4 v[12:13], v[2:5], off
	s_nop 1
	v_add_co_u32_e32 v2, vcc, s52, v10
	s_nop 1
	v_addc_co_u32_e32 v3, vcc, 0, v11, vcc
	s_waitcnt lgkmcnt(0)
; #define LAS __attribute__((address_space(3)))
; DI CP* kparams() { CP* kp = (CP*)__builtin_amdgcn_kernarg_segment_ptr(); asm volatile("" : "+s"(kp)); return kp; }
; DI int lane_id() { int l = __builtin_amdgcn_mbcnt_hi(-1, __builtin_amdgcn_mbcnt_lo(-1, 0)); asm volatile("" : "+v"(l)); return l; }
; #define A_LOAD(kt) do { const size_t ko = (size_t)(kt) * 64; st0 = *(const u32x4*)(kn_src + ko * 2048); st1 = *(const u32x4*)(kn_src + (ko + 32) * 2048); \
;         st2 = *(const u32x4*)(kr_src + ko * 64); st3 = *(const u32x4*)(v_src + ko); st4 = *(const u32x4*)(v_src + ko + (size_t)64 * 8192); } while (0)
; DI void attn_unit(LAS unsigned char* lds, int wid, int b, int h, int qb) {
;     CP& p = *kparams();
;     const int lane = lane_id(), tid = wid * 64 + lane, n = lane & 31, g = lane >> 5;
;     const int q0 = qb * 256 + wid * 32, cq = q0 >> 6, nkt = 4 * qb + 4;
;     const size_t tokq = (size_t)b * SEQ + q0 + n;
;     const bf16_t* Q = WSB(OFF_Q); const bf16_t* KN = WSB(OFF_KN); const bf16_t* KR = WSB(OFF_KR); const bf16_t* VT = WSB(OFF_VT2);
;     bf16x8 qf[12];
; #pragma unroll
;     for (int ks = 0; ks < 12; ++ks) qf[ks] = *(const bf16x8*)(Q + tokq * 3072 + h * 192 + ks * 16 + g * 8);
;     f32x16 o[4];
; #pragma unroll
;     for (int dt = 0; dt < 4; ++dt)
; #pragma unroll
;         for (int i = 0; i < 16; ++i) o[dt][i] = 0.f;
;     float mrow = -__builtin_inff(), lrow = 0.f;
;     const int krow = tid >> 4, kc16 = tid & 15, rrow = tid >> 3, rc8 = tid & 7;
;     const bf16_t* kn_src = KN + ((size_t)b * SEQ + krow) * 2048 + h * 128 + kc16 * 8;
;     const bf16_t* kr_src = KR + ((size_t)b * SEQ + rrow) * 64 + rc8 * 8;
;     const bf16_t* v_src = VT + ((size_t)h * 128 + rrow) * 8192 + (size_t)b * SEQ + rc8 * 8;
;     const int kn_dst = krow * KROW + kc16 * 16, kr_dst = rrow * KROW + 256 + rc8 * 16, v_dst = KBYTES + rrow * VROW + rc8 * 16;
;     u32x4 st0, st1, st2, st3, st4;
;     ...
;     A_LOAD(0); A_WRITE(0); __syncthreads();
;     ...
;     for (int j = 0; j < 8; ++j) { const u32x4 w = *(const LAS u32x4*)(pt_ + (4 * j + (lane >> 4)) * 272 + (lane & 15) * 16); *(u32x4*)(od + (size_t)(4 * j) * 2048) = w; }
;     asm volatile("" ::: "memory");
	global_store_dwordx4 v[2:3], v[6:9], off
	ds_read_b128 v[2:5], v0 offset:49536
	ds_read_b128 v[6:9], v0 offset:50624
	v_add_co_u32_e32 v12, vcc, s53, v10
	s_nop 1
	v_addc_co_u32_e32 v13, vcc, 0, v11, vcc
	s_waitcnt lgkmcnt(1)
	global_store_dwordx4 v[12:13], v[2:5], off
	s_nop 1
	v_add_co_u32_e32 v2, vcc, s54, v10
	s_nop 1
	v_addc_co_u32_e32 v3, vcc, 0, v11, vcc
	s_waitcnt lgkmcnt(0)
	global_store_dwordx4 v[2:3], v[6:9], off
	s_load_dwordx2 s[26:27], s[26:27], 0xa8
	v_add_u32_e32 v0, s28, v187
	v_ashrrev_i32_e32 v24, 3, v0
	v_ashrrev_i32_e32 v25, 31, v24
	v_ashrrev_i32_e32 v22, 4, v0
	v_lshl_add_u64 v[4:5], s[16:17], 0, v[24:25]
	v_ashrrev_i32_e32 v23, 31, v22
	v_lshlrev_b64 v[4:5], 7, v[4:5]
	v_lshlrev_b32_e32 v0, 4, v187
	v_lshl_add_u64 v[2:3], s[16:17], 0, v[22:23]
	s_waitcnt lgkmcnt(0)
	v_lshl_add_u64 v[4:5], s[26:27], 0, v[4:5]
	v_and_b32_e32 v0, 0x70, v0
	v_lshlrev_b64 v[2:3], 12, v[2:3]
	v_lshl_add_u64 v[10:11], v[4:5], 0, v[0:1]
	v_lshl_add_u64 v[4:5], v[24:25], 0, s[4:5]
	v_and_b32_e32 v30, 15, v187
	v_lshl_add_u64 v[2:3], s[26:27], 0, v[2:3]
	v_lshlrev_b64 v[4:5], 14, v[4:5]
	v_lshl_add_u64 v[2:3], v[2:3], 0, s[24:25]
	v_lshlrev_b32_e32 v184, 4, v30
	v_lshl_add_u64 v[4:5], s[26:27], 0, v[4:5]
	v_lshl_add_u64 v[2:3], v[2:3], 0, v[184:185]
	v_lshl_add_u64 v[4:5], s[16:17], 1, v[4:5]
	v_lshl_add_u64 v[18:19], v[4:5], 0, v[0:1]
	v_add_co_u32_e32 v4, vcc, s40, v2
	s_and_b32 s4, s57, 7
	s_nop 0
	v_addc_co_u32_e32 v5, vcc, 0, v3, vcc
	v_add_co_u32_e32 v6, vcc, s41, v2
	s_lshl_b32 s4, s4, 2
	s_lshl_b32 s25, s56, 8
	v_addc_co_u32_e32 v7, vcc, 0, v3, vcc
	s_or_b32 s4, s4, 3
	s_add_i32 s25, s25, s29
	v_add_co_u32_e32 v10, vcc, s42, v10
	v_and_b32_e32 v202, 31, v187
	s_add_u32 s16, s16, s25
	v_addc_co_u32_e32 v11, vcc, 0, v11, vcc
	v_or_b32_e32 v28, s16, v202
	v_mov_b64_e32 v[26:27], s[26:27]
	v_add_co_u32_e32 v14, vcc, s43, v18
	v_ashrrev_i32_e32 v31, 5, v187
	s_addc_u32 s17, s17, 0
	v_mad_u64_u32 v[26:27], s[62:63], v28, s37, v[26:27]
	v_addc_co_u32_e32 v15, vcc, 0, v19, vcc
	v_mad_i32_i24 v27, s17, v200, v27
	s_lshl_b32 s62, s58, 1
	s_mov_b32 s63, s5
	v_lshlrev_b32_e32 v188, 3, v31
	v_add_co_u32_e32 v18, vcc, s44, v18
	v_lshl_add_u64 v[26:27], v[26:27], 0, s[62:63]
	v_ashrrev_i32_e32 v189, 31, v188
	global_load_dwordx4 v[2:5], v[4:5], off
	s_nop 0
	global_load_dwordx4 v[6:9], v[6:7], off
	v_addc_co_u32_e32 v19, vcc, 0, v19, vcc
	v_lshl_add_u64 v[26:27], v[188:189], 1, v[26:27]
	global_load_dwordx4 v[10:13], v[10:11], off
	v_lshl_add_u64 v[28:29], v[26:27], 0, s[8:9]
	v_add_co_u32_e32 v26, vcc, s38, v26
	global_load_dwordx4 v[14:17], v[14:15], off
	s_nop 0
	v_addc_co_u32_e32 v27, vcc, 0, v27, vcc
	global_load_dwordx4 v[18:21], v[18:19], off
	s_nop 0
	global_load_dwordx4 v[152:155], v[28:29], off offset:32
	global_load_dwordx4 v[148:151], v[28:29], off offset:64
	global_load_dwordx4 v[144:147], v[28:29], off offset:96
	global_load_dwordx4 v[140:143], v[28:29], off offset:128
	global_load_dwordx4 v[136:139], v[28:29], off offset:160
	global_load_dwordx4 v[132:135], v[28:29], off offset:192
	global_load_dwordx4 v[128:131], v[28:29], off offset:224
	global_load_dwordx4 v[124:127], v[28:29], off offset:256
	global_load_dwordx4 v[120:123], v[28:29], off offset:288
	global_load_dwordx4 v[116:119], v[28:29], off offset:320
	global_load_dwordx4 v[156:159], v[26:27], off
	global_load_dwordx4 v[112:115], v[28:29], off offset:352
	v_mad_u64_u32 v[190:191], s[62:63], v22, s39, v[184:185]
	v_add_u32_e32 v26, 0, v190
	v_mad_u64_u32 v[192:193], s[62:63], v24, s39, v[0:1]
	s_waitcnt vmcnt(16)
	ds_write_b128 v26, v[2:5]
	s_waitcnt vmcnt(15)
	ds_write_b128 v26, v[6:9] offset:12800
	v_add_u32_e32 v2, 0, v192
	v_mul_lo_u32 v3, v24, s45
	s_lshr_b32 s25, s25, 6
	s_waitcnt vmcnt(14)
	ds_write_b128 v2, v[10:13] offset:256
	v_add_u32_e32 v2, v2, v3
	v_add_u32_e32 v203, v192, v3
	v_add_u32_e32 v3, 0x6400, v2
	v_add_u32_e32 v2, 0x8600, v2
	s_add_u32 s18, s18, s59
	s_waitcnt vmcnt(13)
	ds_write2_b64 v3, v[14:15], v[16:17] offset1:1
	s_waitcnt vmcnt(12)
	ds_write2_b64 v2, v[18:19], v[20:21] offset1:1
	v_lshlrev_b32_e32 v2, 2, v187
	v_xor_b32_e32 v189, 0x80, v2
	v_lshlrev_b64 v[2:3], 14, v[24:25]
	s_addc_u32 s19, s19, 0
	v_lshl_add_u64 v[2:3], s[18:19], 0, v[2:3]
	v_lshl_add_u64 v[194:195], v[2:3], 0, v[0:1]
	v_lshlrev_b64 v[2:3], 7, v[24:25]
	v_lshl_add_u64 v[2:3], s[20:21], 0, v[2:3]
	s_add_u32 s18, s60, s22
	v_lshl_add_u64 v[196:197], v[2:3], 0, v[0:1]
	v_lshlrev_b64 v[2:3], 12, v[22:23]
	s_addc_u32 s19, 0, s23
	v_lshl_add_u64 v[2:3], s[18:19], 0, v[2:3]
	v_mov_b32_e32 v14, v1
	v_mov_b32_e32 v15, v1
	v_lshlrev_b32_e32 v186, 3, v30
	v_lshlrev_b32_e32 v204, 4, v31
	v_lshl_add_u64 v[198:199], v[2:3], 0, v[184:185]
	v_mov_b32_e32 v0, v1
	v_mov_b32_e32 v2, v1
	v_mov_b32_e32 v3, v1
	v_mov_b32_e32 v4, v1
	v_mov_b32_e32 v5, v1
	v_mov_b32_e32 v6, v1
	v_mov_b32_e32 v7, v1
	v_mov_b32_e32 v8, v1
	v_mov_b32_e32 v9, v1
	v_mov_b32_e32 v10, v1
	v_mov_b32_e32 v11, v1
	v_mov_b32_e32 v12, v1
	v_mov_b32_e32 v13, v1
	v_mov_b64_e32 v[30:31], v[14:15]
	v_mov_b64_e32 v[46:47], v[14:15]
	v_mov_b64_e32 v[62:63], v[14:15]
	v_mov_b64_e32 v[78:79], v[14:15]
	s_mov_b32 s57, 0
	v_mul_u32_u24_e32 v193, 0x190, v202
	v_mul_u32_u24_e32 v191, 0x88, v202
	v_mov_b32_e32 v185, 0
	v_mov_b64_e32 v[28:29], v[12:13]
	v_mov_b64_e32 v[26:27], v[10:11]
	v_mov_b64_e32 v[24:25], v[8:9]
	v_mov_b64_e32 v[22:23], v[6:7]
	v_mov_b64_e32 v[20:21], v[4:5]
	v_mov_b64_e32 v[18:19], v[2:3]
	v_mov_b64_e32 v[16:17], v[0:1]
	v_mov_b64_e32 v[44:45], v[12:13]
	v_mov_b64_e32 v[42:43], v[10:11]
	v_mov_b64_e32 v[40:41], v[8:9]
	v_mov_b64_e32 v[38:39], v[6:7]
	v_mov_b64_e32 v[36:37], v[4:5]
	v_mov_b64_e32 v[34:35], v[2:3]
	v_mov_b64_e32 v[32:33], v[0:1]
	v_mov_b64_e32 v[60:61], v[12:13]
	v_mov_b64_e32 v[58:59], v[10:11]
	v_mov_b64_e32 v[56:57], v[8:9]
	v_mov_b64_e32 v[54:55], v[6:7]
	v_mov_b64_e32 v[52:53], v[4:5]
	v_mov_b64_e32 v[50:51], v[2:3]
	v_mov_b64_e32 v[48:49], v[0:1]
	v_mov_b64_e32 v[76:77], v[12:13]
	v_mov_b64_e32 v[74:75], v[10:11]
	v_mov_b64_e32 v[72:73], v[8:9]
	v_mov_b64_e32 v[70:71], v[6:7]
	v_mov_b64_e32 v[68:69], v[4:5]
	v_mov_b64_e32 v[66:67], v[2:3]
	v_mov_b64_e32 v[64:65], v[0:1]
	s_waitcnt lgkmcnt(0)
	v_mov_b32_e32 v216, 0
	v_mov_b32_e32 v217, 0
	v_mov_b32_e32 v218, 0
	v_mov_b32_e32 v219, 0
	v_mov_b32_e32 v220, 0
	v_mov_b32_e32 v221, 0
	v_mov_b32_e32 v222, 0
	v_mov_b32_e32 v223, 0
	v_mov_b32_e32 v224, 0
	v_mov_b32_e32 v225, 0
	v_mov_b32_e32 v226, 0
	v_mov_b32_e32 v227, 0
	v_mov_b32_e32 v228, 0
	v_mov_b32_e32 v229, 0
	v_mov_b32_e32 v230, 0
	v_mov_b32_e32 v231, 0
	s_add_u32 s70, s26, 0x11140000
	s_addc_u32 s71, s27, 0
	s_add_u32 s72, s26, 0x11160000
	s_addc_u32 s73, s27, 0
	s_add_u32 s74, s26, 0x13100000
	s_addc_u32 s75, s27, 0
	s_add_u32 s76, s26, 0x13200000
	s_addc_u32 s77, s27, 0
	s_mov_b64 s[78:79], s[26:27]
	v_add_u32_e32 v238, 0x6400, v203
	v_add_u32_e32 v239, 0x8600, v203
	v_add_u32_e32 v240, 0xa800, v238
	v_add_u32_e32 v241, 0xa800, v239
; #define LAS __attribute__((address_space(3)))
; DI float shfl_xor_l(float v, int lane, int m) { return __int_as_float(__builtin_amdgcn_ds_bpermute((lane ^ m) << 2, __float_as_int(v))); }
; #define A_LOAD(kt) do { const size_t ko = (size_t)(kt) * 64; st0 = *(const u32x4*)(kn_src + ko * 2048); st1 = *(const u32x4*)(kn_src + (ko + 32) * 2048); \
;         st2 = *(const u32x4*)(kr_src + ko * 64); st3 = *(const u32x4*)(v_src + ko); st4 = *(const u32x4*)(v_src + ko + (size_t)64 * 8192); } while (0)
; #define VLD(dst, j, dt) do { LAS unsigned char* va_ = vb + (32 * (dt) + n) * VROW + (16 * (j) + 4 * g) * 2; const u32x2 lo_ = *(const LAS u32x2*)(va_), hi_ = *(const LAS u32x2*)(va_ + 16); dst = (u32x4){lo_.x, lo_.y, hi_.x, hi_.y}; } while (0)
; DI void attn_unit(LAS unsigned char* lds, int wid, int b, int h, int qb) {
;     ...
;     for (int kt = 0; kt < nkt; ++kt) {
;         const int buf = kt & 1;
;         if (kt + 1 < nkt) A_LOAD(kt + 1);
;         if (kt <= cq) {
;             LAS unsigned char* kb = lds + buf * ABUF; LAS unsigned char* vb = kb + KBYTES;
;             f32x16 s0, s1;
; #pragma unroll
;             for (int i = 0; i < 16; ++i) { s0[i] = 0.f; s1[i] = 0.f; }
;     ...
;             bf16x8 ka[3][2];
;             ka[0][0] = KLD(0, 0); ka[0][1] = KLD(0, 1); ka[1][0] = KLD(1, 0); ka[1][1] = KLD(1, 1);
; #pragma unroll
;             for (int ks = 0; ks < 12; ++ks) {
;                 if (ks + 2 < 12) { ka[(ks + 2) % 3][0] = KLD(ks + 2, 0); ka[(ks + 2) % 3][1] = KLD(ks + 2, 1); }
;                 s0 = __builtin_amdgcn_mfma_f32_32x32x16_bf16(ka[ks % 3][0], qf[ks], s0, 0, 0, 0); s1 = __builtin_amdgcn_mfma_f32_32x32x16_bf16(ka[ks % 3][1], qf[ks], s1, 0, 0, 0);
;                 __builtin_amdgcn_sched_barrier(0); }
;             u32x4 vf[2][4];
; #pragma unroll
;             for (int dt = 0; dt < 4; ++dt) VLD(vf[0][dt], 0, dt);
;             float mx = s0[0];
; #pragma unroll
;             for (int i = 1; i < 16; ++i) mx = fmaxf(mx, s0[i]);
; #pragma unroll
;             for (int i = 0; i < 16; ++i) mx = fmaxf(mx, s1[i]);
;             mx = fmaxf(mx, shfl_xor_l(mx, lane, 32));
.Lrot2_head:
	s_barrier
.LBB0_1091:
	s_and_b32 s18, s57, 1
	global_load_dwordx4 v[2:5], v198, s[70:71]
	global_load_dwordx4 v[6:9], v198, s[72:73]
	global_load_dwordx4 v[10:13], v196, s[78:79]
	global_load_dwordx4 v[160:163], v194, s[74:75] offset:128
	global_load_dwordx4 v[164:167], v194, s[76:77] offset:128
	s_cmp_gt_u32 s57, s25
	s_cbranch_scc1 .LBB0_1095
	s_mul_i32 s19, s18, 0xa800
	s_add_i32 s19, s19, 0
	v_add3_u32 v0, s19, v193, v204
	ds_read_b128 v[80:83], v0
	ds_read_b128 v[168:171], v0 offset:32
	ds_read_b128 v[96:99], v0 offset:12800
	ds_read_b128 v[174:177], v0 offset:64
	ds_read_b128 v[178:181], v0 offset:12832
	ds_read_b128 v[206:209], v0 offset:12864
	s_waitcnt vmcnt(6) lgkmcnt(3)
	v_mfma_f32_32x32x16_bf16 v[96:111], v[96:99], v[156:159], v[216:231]
	v_mfma_f32_32x32x16_bf16 v[80:95], v[80:83], v[156:159], v[216:231]
	v_mfma_f32_32x32x16_bf16 v[80:95], v[168:171], v[152:155], v[80:95]
	ds_read_b128 v[168:171], v0 offset:96
	ds_read_b128 v[210:213], v0 offset:12896
	s_waitcnt lgkmcnt(3)
	v_mfma_f32_32x32x16_bf16 v[96:111], v[178:181], v[152:155], v[96:111]
	v_mfma_f32_32x32x16_bf16 v[80:95], v[174:177], v[148:151], v[80:95]
	ds_read_b128 v[174:177], v0 offset:128
	ds_read_b128 v[178:181], v0 offset:12928
	s_waitcnt lgkmcnt(4)
	v_mfma_f32_32x32x16_bf16 v[96:111], v[206:209], v[148:151], v[96:111]
	s_waitcnt lgkmcnt(3)
	v_mfma_f32_32x32x16_bf16 v[80:95], v[168:171], v[144:147], v[80:95]
	ds_read_b128 v[168:171], v0 offset:160
	ds_read_b128 v[206:209], v0 offset:12960
	s_waitcnt lgkmcnt(4)
	v_mfma_f32_32x32x16_bf16 v[96:111], v[210:213], v[144:147], v[96:111]
	s_waitcnt lgkmcnt(3)
	v_mfma_f32_32x32x16_bf16 v[80:95], v[174:177], v[140:143], v[80:95]
	ds_read_b128 v[174:177], v0 offset:192
	ds_read_b128 v[210:213], v0 offset:12992
	s_waitcnt lgkmcnt(4)
	v_mfma_f32_32x32x16_bf16 v[96:111], v[178:181], v[140:143], v[96:111]
	s_waitcnt lgkmcnt(3)
	v_mfma_f32_32x32x16_bf16 v[80:95], v[168:171], v[136:139], v[80:95]
	ds_read_b128 v[168:171], v0 offset:224
	ds_read_b128 v[178:181], v0 offset:13024
	s_waitcnt lgkmcnt(4)
	v_mfma_f32_32x32x16_bf16 v[96:111], v[206:209], v[136:139], v[96:111]
	s_waitcnt lgkmcnt(3)
	v_mfma_f32_32x32x16_bf16 v[80:95], v[174:177], v[132:135], v[80:95]
	ds_read_b128 v[174:177], v0 offset:256
	ds_read_b128 v[206:209], v0 offset:13056
	s_waitcnt lgkmcnt(4)
	v_mfma_f32_32x32x16_bf16 v[96:111], v[210:213], v[132:135], v[96:111]
	s_waitcnt lgkmcnt(3)
	v_mfma_f32_32x32x16_bf16 v[80:95], v[168:171], v[128:131], v[80:95]
	ds_read_b128 v[168:171], v0 offset:288
	ds_read_b128 v[210:213], v0 offset:13088
	s_waitcnt lgkmcnt(4)
	v_mfma_f32_32x32x16_bf16 v[96:111], v[178:181], v[128:131], v[96:111]
	s_waitcnt lgkmcnt(3)
	v_mfma_f32_32x32x16_bf16 v[80:95], v[174:177], v[124:127], v[80:95]
	ds_read_b128 v[174:177], v0 offset:320
	ds_read_b128 v[178:181], v0 offset:13120
	s_waitcnt lgkmcnt(4)
	v_mfma_f32_32x32x16_bf16 v[96:111], v[206:209], v[124:127], v[96:111]
	s_waitcnt lgkmcnt(3)
	v_mfma_f32_32x32x16_bf16 v[80:95], v[168:171], v[120:123], v[80:95]
	ds_read_b128 v[168:171], v0 offset:352
	ds_read_b128 v[206:209], v0 offset:13152
	s_waitcnt lgkmcnt(4)
	v_mfma_f32_32x32x16_bf16 v[96:111], v[210:213], v[120:123], v[96:111]
	s_waitcnt lgkmcnt(3)
	v_mfma_f32_32x32x16_bf16 v[80:95], v[174:177], v[116:119], v[80:95]
	s_waitcnt lgkmcnt(2)
	v_mfma_f32_32x32x16_bf16 v[96:111], v[178:181], v[116:119], v[96:111]
	s_waitcnt vmcnt(5) lgkmcnt(1)
	v_mfma_f32_32x32x16_bf16 v[80:95], v[168:171], v[112:115], v[80:95]
	v_add3_u32 v173, s19, v188, v191
	v_add_u32_e32 v15, 0x6000, v173
	v_add_u32_e32 v205, 0x7000, v173
	ds_read2_b64 v[168:171], v15 offset0:128 offset1:130
	ds_read2_b64 v[180:183], v205 offset0:160 offset1:162
	s_nop 5
	v_max_f32_e32 v0, v80, v81
	s_waitcnt lgkmcnt(2)
	v_mfma_f32_32x32x16_bf16 v[96:111], v[206:209], v[112:115], v[96:111]
	v_max3_f32 v0, v0, v82, v83
	v_max3_f32 v0, v0, v84, v85
	v_max3_f32 v0, v0, v86, v87
	v_max3_f32 v0, v0, v88, v89
	v_max3_f32 v0, v0, v90, v91
	v_max3_f32 v0, v0, v92, v93
	v_max3_f32 v0, v0, v94, v95
	s_nop 4
	v_max3_f32 v0, v0, v96, v97
	v_max3_f32 v0, v0, v98, v99
	v_max3_f32 v0, v0, v100, v101
	v_max3_f32 v0, v0, v102, v103
	v_max3_f32 v0, v0, v104, v105
	v_max3_f32 v0, v0, v106, v107
	v_max3_f32 v0, v0, v108, v109
	v_max3_f32 v0, v0, v110, v111
	v_add_u32_e32 v206, 0x8000, v173
	v_add_u32_e32 v207, 0x9000, v173
	ds_read2_b64 v[176:179], v206 offset0:192 offset1:194
	v_cmp_lt_f32_e32 vcc, 0x41000000, v0
	ds_read2_b64 v[172:175], v207 offset0:224 offset1:226
	s_cmp_eq_u32 s57, 0
	s_cbranch_scc1 .Lfold_2_upd
	s_cbranch_vccnz .Lfold_2_upd

; DI void attn_unit(LAS unsigned char* lds, int wid, int b, int h, int qb) {
;     ...
;         if (kt + 1 < nkt) A_WRITE(buf ^ 1);
;         __syncthreads();
.Lw2_join:
	s_cmp_eq_u32 s4, s57
	s_waitcnt lgkmcnt(0)
	s_cbranch_scc1 .Lrot2_exit
	s_branch .Lrot2_head

; DI void attn_unit(LAS unsigned char* lds, int wid, int b, int h, int qb) {
;     ...
;             if (__builtin_amdgcn_ballot_w64(alpha != 1.f) != 0ull) {
; #pragma unroll
;                 for (int dt = 0; dt < 4; ++dt)
; #pragma unroll
;                     for (int i = 0; i < 16; ++i) o[dt][i] *= alpha;
;             }
;     ...
;         __syncthreads();
.Lfold_2_go:
	s_nop 0
	v_pk_mul_f32 v[78:79], v[78:79], v[0:1] op_sel_hi:[1,0]
	v_pk_mul_f32 v[76:77], v[76:77], v[0:1] op_sel_hi:[1,0]
	v_pk_mul_f32 v[74:75], v[74:75], v[0:1] op_sel_hi:[1,0]
	v_pk_mul_f32 v[72:73], v[72:73], v[0:1] op_sel_hi:[1,0]
	v_pk_mul_f32 v[70:71], v[70:71], v[0:1] op_sel_hi:[1,0]
	v_pk_mul_f32 v[68:69], v[68:69], v[0:1] op_sel_hi:[1,0]
	v_pk_mul_f32 v[66:67], v[66:67], v[0:1] op_sel_hi:[1,0]
	v_pk_mul_f32 v[64:65], v[64:65], v[0:1] op_sel_hi:[1,0]
	v_pk_mul_f32 v[62:63], v[62:63], v[0:1] op_sel_hi:[1,0]
	v_pk_mul_f32 v[60:61], v[60:61], v[0:1] op_sel_hi:[1,0]
	v_pk_mul_f32 v[58:59], v[58:59], v[0:1] op_sel_hi:[1,0]
	v_pk_mul_f32 v[56:57], v[56:57], v[0:1] op_sel_hi:[1,0]
	v_pk_mul_f32 v[54:55], v[54:55], v[0:1] op_sel_hi:[1,0]
	v_pk_mul_f32 v[52:53], v[52:53], v[0:1] op_sel_hi:[1,0]
	v_pk_mul_f32 v[50:51], v[50:51], v[0:1] op_sel_hi:[1,0]
	v_pk_mul_f32 v[48:49], v[48:49], v[0:1] op_sel_hi:[1,0]
	v_pk_mul_f32 v[46:47], v[46:47], v[0:1] op_sel_hi:[1,0]
	v_pk_mul_f32 v[44:45], v[44:45], v[0:1] op_sel_hi:[1,0]
	v_pk_mul_f32 v[42:43], v[42:43], v[0:1] op_sel_hi:[1,0]
	v_pk_mul_f32 v[40:41], v[40:41], v[0:1] op_sel_hi:[1,0]
	v_pk_mul_f32 v[38:39], v[38:39], v[0:1] op_sel_hi:[1,0]
	v_pk_mul_f32 v[36:37], v[36:37], v[0:1] op_sel_hi:[1,0]
	v_pk_mul_f32 v[34:35], v[34:35], v[0:1] op_sel_hi:[1,0]
	v_pk_mul_f32 v[32:33], v[32:33], v[0:1] op_sel_hi:[1,0]
	v_pk_mul_f32 v[30:31], v[30:31], v[0:1] op_sel_hi:[1,0]
	v_pk_mul_f32 v[28:29], v[28:29], v[0:1] op_sel_hi:[1,0]
	v_pk_mul_f32 v[26:27], v[26:27], v[0:1] op_sel_hi:[1,0]
	v_pk_mul_f32 v[24:25], v[24:25], v[0:1] op_sel_hi:[1,0]
	v_pk_mul_f32 v[22:23], v[22:23], v[0:1] op_sel_hi:[1,0]
	v_pk_mul_f32 v[20:21], v[20:21], v[0:1] op_sel_hi:[1,0]
	v_pk_mul_f32 v[18:19], v[18:19], v[0:1] op_sel_hi:[1,0]
	v_pk_mul_f32 v[16:17], v[16:17], v[0:1] op_sel_hi:[1,0]
	v_sub_f32_e32 v80, v80, v237
	v_sub_f32_e32 v96, v96, v237
	v_sub_f32_e32 v81, v81, v237
	v_sub_f32_e32 v97, v97, v237
	v_sub_f32_e32 v82, v82, v237
	v_sub_f32_e32 v98, v98, v237
	v_sub_f32_e32 v83, v83, v237
	v_sub_f32_e32 v99, v99, v237
	v_sub_f32_e32 v84, v84, v237
	v_sub_f32_e32 v100, v100, v237
	v_sub_f32_e32 v85, v85, v237
	v_sub_f32_e32 v101, v101, v237
	v_sub_f32_e32 v86, v86, v237
	v_sub_f32_e32 v102, v102, v237
	v_sub_f32_e32 v87, v87, v237
	v_sub_f32_e32 v103, v103, v237
	v_sub_f32_e32 v88, v88, v237
	v_sub_f32_e32 v104, v104, v237
	v_sub_f32_e32 v89, v89, v237
	v_sub_f32_e32 v105, v105, v237
	v_sub_f32_e32 v90, v90, v237
	v_sub_f32_e32 v106, v106, v237
	v_sub_f32_e32 v91, v91, v237
	v_sub_f32_e32 v107, v107, v237
	v_sub_f32_e32 v92, v92, v237
	v_sub_f32_e32 v108, v108, v237
	v_sub_f32_e32 v93, v93, v237
	v_sub_f32_e32 v109, v109, v237
	v_sub_f32_e32 v94, v94, v237
	v_sub_f32_e32 v110, v110, v237
	v_sub_f32_e32 v95, v95, v237
	v_sub_f32_e32 v111, v111, v237
	v_sub_f32_e32 v216, v216, v237
	v_sub_f32_e32 v217, v217, v237
	v_sub_f32_e32 v218, v218, v237
	v_sub_f32_e32 v219, v219, v237
	v_sub_f32_e32 v220, v220, v237
	v_sub_f32_e32 v221, v221, v237
	v_sub_f32_e32 v222, v222, v237
	v_sub_f32_e32 v223, v223, v237
	v_sub_f32_e32 v224, v224, v237
	v_sub_f32_e32 v225, v225, v237
	v_sub_f32_e32 v226, v226, v237
	v_sub_f32_e32 v227, v227, v237
	v_sub_f32_e32 v228, v228, v237
	v_sub_f32_e32 v229, v229, v237
	v_sub_f32_e32 v230, v230, v237
	v_sub_f32_e32 v231, v231, v237
	v_mul_f32_e32 v185, v185, v0
	s_branch .LBB0_1094
.Lrot2_exit:
	s_barrier
; #define LAS __attribute__((address_space(3)))
; DI float shfl_xor_l(float v, int lane, int m) { return __int_as_float(__builtin_amdgcn_ds_bpermute((lane ^ m) << 2, __float_as_int(v))); }
; #define A_LOAD(kt) do { const size_t ko = (size_t)(kt) * 64; st0 = *(const u32x4*)(kn_src + ko * 2048); st1 = *(const u32x4*)(kn_src + (ko + 32) * 2048); \
;         st2 = *(const u32x4*)(kr_src + ko * 64); st3 = *(const u32x4*)(v_src + ko); st4 = *(const u32x4*)(v_src + ko + (size_t)64 * 8192); } while (0)
; #define VLD(dst, j, dt) do { LAS unsigned char* va_ = vb + (32 * (dt) + n) * VROW + (16 * (j) + 4 * g) * 2; const u32x2 lo_ = *(const LAS u32x2*)(va_), hi_ = *(const LAS u32x2*)(va_ + 16); dst = (u32x4){lo_.x, lo_.y, hi_.x, hi_.y}; } while (0)
; DI void attn_unit(LAS unsigned char* lds, int wid, int b, int h, int qb) {
;     ...
;         if (kt + 1 < nkt) A_LOAD(kt + 1);
;         if (kt <= cq) {
;             LAS unsigned char* kb = lds + buf * ABUF; LAS unsigned char* vb = kb + KBYTES;
;             f32x16 s0, s1;
; #pragma unroll
;             for (int i = 0; i < 16; ++i) { s0[i] = 0.f; s1[i] = 0.f; }
;     ...
;             bf16x8 ka[3][2];
;             ka[0][0] = KLD(0, 0); ka[0][1] = KLD(0, 1); ka[1][0] = KLD(1, 0); ka[1][1] = KLD(1, 1);
; #pragma unroll
;             for (int ks = 0; ks < 12; ++ks) {
;                 if (ks + 2 < 12) { ka[(ks + 2) % 3][0] = KLD(ks + 2, 0); ka[(ks + 2) % 3][1] = KLD(ks + 2, 1); }
;                 s0 = __builtin_amdgcn_mfma_f32_32x32x16_bf16(ka[ks % 3][0], qf[ks], s0, 0, 0, 0); s1 = __builtin_amdgcn_mfma_f32_32x32x16_bf16(ka[ks % 3][1], qf[ks], s1, 0, 0, 0);
;                 __builtin_amdgcn_sched_barrier(0); }
;             u32x4 vf[2][4];
; #pragma unroll
;             for (int dt = 0; dt < 4; ++dt) VLD(vf[0][dt], 0, dt);
;             float mx = s0[0];
; #pragma unroll
;             for (int i = 1; i < 16; ++i) mx = fmaxf(mx, s0[i]);
; #pragma unroll
;             for (int i = 0; i < 16; ++i) mx = fmaxf(mx, s1[i]);
;             mx = fmaxf(mx, shfl_xor_l(mx, lane, 32));
.LBB0_1098:
	s_lshl_b32 s18, s56, 2
	s_or_b32 s18, s18, 2
	s_cmp_ge_u32 s18, s25
	s_cbranch_scc1 .LBB0_1077
	s_bitcmp1_b32 s4, 0
	s_cselect_b32 s4, 0xa800, 0
	s_add_i32 s4, s4, 0
	v_add3_u32 v0, s4, v193, v204
	ds_read_b128 v[2:5], v0
	ds_read_b128 v[6:9], v0 offset:32
	s_waitcnt lgkmcnt(1)
	v_mfma_f32_32x32x16_bf16 v[80:95], v[2:5], v[156:159], v[216:231]
	ds_read_b128 v[2:5], v0 offset:12800
	ds_read_b128 v[10:13], v0 offset:64
	ds_read_b128 v[160:163], v0 offset:12832
	ds_read_b128 v[164:167], v0 offset:12864
	s_waitcnt lgkmcnt(3)
	v_mfma_f32_32x32x16_bf16 v[96:111], v[2:5], v[156:159], v[216:231]
	v_mfma_f32_32x32x16_bf16 v[80:95], v[6:9], v[152:155], v[80:95]
	ds_read_b128 v[2:5], v0 offset:96
	ds_read_b128 v[6:9], v0 offset:12896
	s_waitcnt lgkmcnt(3)
	v_mfma_f32_32x32x16_bf16 v[96:111], v[160:163], v[152:155], v[96:111]
	v_mfma_f32_32x32x16_bf16 v[80:95], v[10:13], v[148:151], v[80:95]
	ds_read_b128 v[10:13], v0 offset:128
	ds_read_b128 v[152:155], v0 offset:12928
	s_waitcnt lgkmcnt(4)
	v_mfma_f32_32x32x16_bf16 v[96:111], v[164:167], v[148:151], v[96:111]
	s_waitcnt lgkmcnt(3)
	v_mfma_f32_32x32x16_bf16 v[80:95], v[2:5], v[144:147], v[80:95]
	ds_read_b128 v[2:5], v0 offset:160
	ds_read_b128 v[148:151], v0 offset:12960
	s_waitcnt lgkmcnt(4)
	v_mfma_f32_32x32x16_bf16 v[96:111], v[6:9], v[144:147], v[96:111]
	s_waitcnt lgkmcnt(3)
	v_mfma_f32_32x32x16_bf16 v[80:95], v[10:13], v[140:143], v[80:95]
	ds_read_b128 v[6:9], v0 offset:192
	ds_read_b128 v[10:13], v0 offset:12992
	s_waitcnt lgkmcnt(4)
	v_mfma_f32_32x32x16_bf16 v[96:111], v[152:155], v[140:143], v[96:111]
	s_waitcnt lgkmcnt(3)
	v_mfma_f32_32x32x16_bf16 v[80:95], v[2:5], v[136:139], v[80:95]
	ds_read_b128 v[2:5], v0 offset:224
	ds_read_b128 v[140:143], v0 offset:13024
	s_waitcnt lgkmcnt(4)
	v_mfma_f32_32x32x16_bf16 v[96:111], v[148:151], v[136:139], v[96:111]
	s_waitcnt lgkmcnt(3)
	v_mfma_f32_32x32x16_bf16 v[80:95], v[6:9], v[132:135], v[80:95]
	ds_read_b128 v[6:9], v0 offset:256
	ds_read_b128 v[136:139], v0 offset:13056
	s_waitcnt lgkmcnt(4)
	v_mfma_f32_32x32x16_bf16 v[96:111], v[10:13], v[132:135], v[96:111]
	s_waitcnt lgkmcnt(3)
	v_mfma_f32_32x32x16_bf16 v[80:95], v[2:5], v[128:131], v[80:95]
	ds_read_b128 v[2:5], v0 offset:288
	ds_read_b128 v[10:13], v0 offset:13088
	s_waitcnt lgkmcnt(4)
	v_mfma_f32_32x32x16_bf16 v[96:111], v[140:143], v[128:131], v[96:111]
	s_waitcnt lgkmcnt(3)
	v_mfma_f32_32x32x16_bf16 v[80:95], v[6:9], v[124:127], v[80:95]
	ds_read_b128 v[6:9], v0 offset:320
	ds_read_b128 v[128:131], v0 offset:13120
	s_waitcnt lgkmcnt(4)
	v_mfma_f32_32x32x16_bf16 v[96:111], v[136:139], v[124:127], v[96:111]
	s_waitcnt lgkmcnt(3)
	v_mfma_f32_32x32x16_bf16 v[80:95], v[2:5], v[120:123], v[80:95]
	ds_read_b128 v[2:5], v0 offset:352
	ds_read_b128 v[124:127], v0 offset:13152
	s_waitcnt lgkmcnt(4)
	v_mfma_f32_32x32x16_bf16 v[96:111], v[10:13], v[120:123], v[96:111]
	s_waitcnt lgkmcnt(3)
	v_mfma_f32_32x32x16_bf16 v[80:95], v[6:9], v[116:119], v[80:95]
	s_waitcnt lgkmcnt(2)
	v_mfma_f32_32x32x16_bf16 v[96:111], v[128:131], v[116:119], v[96:111]
	s_waitcnt lgkmcnt(1)
	v_mfma_f32_32x32x16_bf16 v[80:95], v[2:5], v[112:115], v[80:95]
	v_add_u32_e32 v0, s4, v188
	v_add_u32_e32 v6, v0, v191
	v_add_u32_e32 v15, 0x6000, v6
	v_add_u32_e32 v116, 0x7000, v6
	v_add_u32_e32 v117, 0x8000, v6
	ds_read2_b64 v[2:5], v15 offset0:128 offset1:130
	ds_read2_b64 v[10:13], v117 offset0:192 offset1:194
	s_nop 4
	v_max_f32_e32 v0, v80, v81
	s_waitcnt lgkmcnt(2)
	v_mfma_f32_32x32x16_bf16 v[96:111], v[124:127], v[112:115], v[96:111]
	v_max3_f32 v0, v0, v82, v83
	v_max3_f32 v0, v0, v84, v85
	v_max3_f32 v0, v0, v86, v87
	v_max3_f32 v0, v0, v88, v89
	v_max3_f32 v0, v0, v90, v91
	v_max3_f32 v0, v0, v92, v93
	v_max3_f32 v0, v0, v94, v95
	s_nop 4
	v_max3_f32 v0, v0, v96, v97
	v_max3_f32 v0, v0, v98, v99
	v_max3_f32 v0, v0, v100, v101
	v_max3_f32 v0, v0, v102, v103
	v_max3_f32 v0, v0, v104, v105
	v_max3_f32 v0, v0, v106, v107
	v_max3_f32 v0, v0, v108, v109
	v_max3_f32 v0, v0, v110, v111
	ds_bpermute_b32 v7, v189, v0
	ds_read2_b64 v[112:115], v116 offset0:160 offset1:162
	s_waitcnt lgkmcnt(1)
	v_max_f32_e32 v237, v0, v7
	v_add_u32_e32 v14, 0x9000, v6
	v_cmp_lt_f32_e32 vcc, 0x41000000, v237
	ds_read2_b64 v[6:9], v14 offset0:224 offset1:226
	s_cbranch_vccz .Lfold_3_keep
